# v34 + scan loaders with four register sets (operand loads three steps ahead)
# speedup vs baseline: 1.0039x; 1.0039x over previous
; #define GS_BAR() asm volatile("s_waitcnt lgkmcnt(0)\n\ts_barrier" ::: "memory")
; #define GS_LOADU(n) do { const bf16_t* up_ = gu + ((size_t)((h * 128 + (n)) * 4 + half) * 2) * 1024 + lane * 16; \
;     _Pragma("unroll") for (int tb_ = 0; tb_ < 2; ++tb_) { U[tb_][0] = *(const u32x4*)(up_ + tb_ * 1024); U[tb_][1] = *(const u32x4*)(up_ + tb_ * 1024 + 8); } \
;     gl_next = __expf(glast[h * 128 + (n)]); } while (0)
; __device__ __forceinline__ void gdn_scan_item(const Ctx& a, int l, int b, int h, int half, LAS unsigned char* lds, int variant) {
;     ...
;     u32x4 pfA[14], pfB[14];
;     const unsigned offWQ = (unsigned)(((u >> 4) * 512 + (u & 15) * 8) * 2), offKT = (unsigned)(((u >> 3) * 64 + (u & 7) * 8) * 2);
;     ...
;     f32x16 S[4];
; #pragma unroll
;     for (int kb = 0; kb < 4; ++kb)
; #pragma unroll
;         for (int r = 0; r < 16; ++r) S[kb][r] = 0.f;
;     const int dv0 = half * 32;
;     u32x4 U[2][2]; float gl_next = 0.f;
;     ...
;     if (loader) { GS_LOAD(0, pfA); GS_STORE(0, pfA); GS_LOAD(1, pfB); } else if (wv < 1) { GS_LOADU(0); }
;     __syncthreads();
;     if (loader) {
;         for (int n = 0; n < 128; n += 2) {
;             const int c2 = (n + 2 < 128) ? n + 2 : 127, c3 = (n + 3 < 128) ? n + 3 : 127;
;             if (variant != 1) { GS_LOAD(c2, pfA); GS_STORE(1, pfB); }
;             GS_BAR();
;             if (variant != 1) { GS_LOAD(c3, pfB); GS_STORE(0, pfA); }
;             GS_BAR();
;         }
.LBB0_157:
	s_or_saveexec_b64 s[0:1], s[0:1]
	s_movk_i32 s46, 0x2000
	s_movk_i32 s47, 0x4000
	s_mov_b32 s48, 0x8000
	s_movk_i32 s49, 0x3000
	s_movk_i32 s50, 0x1000
	s_mov_b32 s51, 0xc000
	s_mov_b32 s52, 0x8400
	s_xor_b64 exec, exec, s[0:1]
	s_cbranch_execz .LBB0_160
	s_waitcnt vmcnt(0)
	v_subrev_u32_e32 v192, 0x100, v179
	v_lshrrev_b32_e32 v143, 4, v192
	v_lshlrev_b32_e32 v143, 10, v143
	v_and_b32_e32 v181, 15, v192
	v_lshl_add_u32 v143, v181, 4, v143
	v_lshrrev_b32_e32 v1, 4, v192
	v_mul_u32_u24_e32 v1, 0x108, v1
	v_lshl_add_u32 v1, v181, 4, v1
	v_add_u32_e32 v1, 0xea00, v1
	v_lshrrev_b32_e32 v142, 3, v192
	v_mul_u32_u24_e32 v142, 0x88, v142
	v_and_b32_e32 v181, 7, v192
	v_lshl_add_u32 v142, v181, 4, v142
	v_add_u32_e32 v142, 0x16e00, v142
	v_lshlrev_b32_e32 v181, 4, v192
	s_lshr_b32 s30, s2, 2
	s_lshl_b32 s8, s30, 8
	s_add_u32 s36, s16, 0xf104200
	s_addc_u32 s37, s17, 0
	s_add_u32 s36, s36, s8
	s_addc_u32 s37, s37, 0
	s_add_u32 s38, s16, 0xf904200
	s_addc_u32 s39, s17, 0
	s_add_u32 s38, s38, s8
	s_addc_u32 s39, s39, 0
	s_lshl_b32 s8, s30, 21
	s_add_u32 s40, s16, 0x100f8200
	s_addc_u32 s41, s17, 0
	s_add_u32 s40, s40, s8
	s_addc_u32 s41, s41, 0
	s_lshl_b32 s8, s30, 20
	s_add_u32 s42, s16, 0x108f6200
	s_addc_u32 s43, s17, 0
	s_add_u32 s42, s42, s8
	s_addc_u32 s43, s43, 0
	s_mov_b32 s26, 1
	s_mov_b64 s[46:47], s[36:37]
	global_load_dwordx4 v[58:61], v143, s[46:47]
	s_add_u32 s46, s46, 0x4000
	s_addc_u32 s47, s47, 0
	global_load_dwordx4 v[62:65], v143, s[46:47]
	s_add_u32 s46, s46, 0x4000
	s_addc_u32 s47, s47, 0
	global_load_dwordx4 v[66:69], v143, s[46:47]
	s_add_u32 s46, s46, 0x4000
	s_addc_u32 s47, s47, 0
	global_load_dwordx4 v[70:73], v143, s[46:47]
	s_mov_b64 s[46:47], s[38:39]
	global_load_dwordx4 v[74:77], v143, s[46:47]
	s_add_u32 s46, s46, 0x4000
	s_addc_u32 s47, s47, 0
	global_load_dwordx4 v[78:81], v143, s[46:47]
	s_add_u32 s46, s46, 0x4000
	s_addc_u32 s47, s47, 0
	global_load_dwordx4 v[82:85], v143, s[46:47]
	s_add_u32 s46, s46, 0x4000
	s_addc_u32 s47, s47, 0
	global_load_dwordx4 v[86:89], v143, s[46:47]
	s_mov_b64 s[46:47], s[40:41]
	global_load_dwordx4 v[90:93], v181, s[46:47]
	s_add_u32 s46, s46, 0x1000
	s_addc_u32 s47, s47, 0
	global_load_dwordx4 v[94:97], v181, s[46:47]
	s_add_u32 s46, s46, 0x1000
	s_addc_u32 s47, s47, 0
	global_load_dwordx4 v[98:101], v181, s[46:47]
	s_add_u32 s46, s46, 0x1000
	s_addc_u32 s47, s47, 0
	global_load_dwordx4 v[102:105], v181, s[46:47]
	s_mov_b64 s[46:47], s[42:43]
	global_load_dwordx4 v[106:109], v181, s[46:47]
	s_add_u32 s46, s46, 0x1000
	s_addc_u32 s47, s47, 0
	global_load_dwordx4 v[110:113], v181, s[46:47]
	s_cmp_lt_u32 s26, 127
	s_cselect_b32 s8, 0x10000, 0
	s_cselect_b32 s12, 0x4000, 0
	s_cselect_b32 s13, 0x2000, 0
	s_addc_u32 s26, s26, 0
	s_add_u32 s36, s36, s8
	s_addc_u32 s37, s37, 0
	s_add_u32 s38, s38, s8
	s_addc_u32 s39, s39, 0
	s_add_u32 s40, s40, s12
	s_addc_u32 s41, s41, 0
	s_add_u32 s42, s42, s13
	s_addc_u32 s43, s43, 0
	s_mov_b64 s[46:47], s[36:37]
	global_load_dwordx4 v[114:117], v143, s[46:47]
	s_add_u32 s46, s46, 0x4000
	s_addc_u32 s47, s47, 0
	global_load_dwordx4 v[118:121], v143, s[46:47]
	s_add_u32 s46, s46, 0x4000
	s_addc_u32 s47, s47, 0
	global_load_dwordx4 v[122:125], v143, s[46:47]
	s_add_u32 s46, s46, 0x4000
	s_addc_u32 s47, s47, 0
	global_load_dwordx4 v[126:129], v143, s[46:47]
	s_mov_b64 s[46:47], s[38:39]
	global_load_dwordx4 v[130:133], v143, s[46:47]
	s_add_u32 s46, s46, 0x4000
	s_addc_u32 s47, s47, 0
	global_load_dwordx4 v[134:137], v143, s[46:47]
	s_add_u32 s46, s46, 0x4000
	s_addc_u32 s47, s47, 0
	global_load_dwordx4 v[138:141], v143, s[46:47]
	s_add_u32 s46, s46, 0x4000
	s_addc_u32 s47, s47, 0
	global_load_dwordx4 v[146:149], v143, s[46:47]
	s_mov_b64 s[46:47], s[40:41]
	global_load_dwordx4 v[150:153], v181, s[46:47]
	s_add_u32 s46, s46, 0x1000
	s_addc_u32 s47, s47, 0
	global_load_dwordx4 v[154:157], v181, s[46:47]
	s_add_u32 s46, s46, 0x1000
	s_addc_u32 s47, s47, 0
	global_load_dwordx4 v[158:161], v181, s[46:47]
	s_add_u32 s46, s46, 0x1000
	s_addc_u32 s47, s47, 0
	global_load_dwordx4 v[162:165], v181, s[46:47]
	s_mov_b64 s[46:47], s[42:43]
	global_load_dwordx4 v[166:169], v181, s[46:47]
	s_add_u32 s46, s46, 0x1000
	s_addc_u32 s47, s47, 0
	global_load_dwordx4 v[170:173], v181, s[46:47]
	s_cmp_lt_u32 s26, 127
	s_cselect_b32 s8, 0x10000, 0
	s_cselect_b32 s12, 0x4000, 0
	s_cselect_b32 s13, 0x2000, 0
	s_addc_u32 s26, s26, 0
	s_add_u32 s36, s36, s8
	s_addc_u32 s37, s37, 0
	s_add_u32 s38, s38, s8
	s_addc_u32 s39, s39, 0
	s_add_u32 s40, s40, s12
	s_addc_u32 s41, s41, 0
	s_add_u32 s42, s42, s13
	s_addc_u32 s43, s43, 0
	s_mov_b64 s[46:47], s[36:37]
	global_load_dwordx4 v[174:177], v143, s[46:47]
	s_add_u32 s46, s46, 0x4000
	s_addc_u32 s47, s47, 0
	global_load_dwordx4 v[184:187], v143, s[46:47]
	s_add_u32 s46, s46, 0x4000
	s_addc_u32 s47, s47, 0
	global_load_dwordx4 v[188:191], v143, s[46:47]
	s_add_u32 s46, s46, 0x4000
	s_addc_u32 s47, s47, 0
	global_load_dwordx4 v[200:203], v143, s[46:47]
	s_mov_b64 s[46:47], s[38:39]
	global_load_dwordx4 v[204:207], v143, s[46:47]
	s_add_u32 s46, s46, 0x4000
	s_addc_u32 s47, s47, 0
	global_load_dwordx4 v[208:211], v143, s[46:47]
	s_add_u32 s46, s46, 0x4000
	s_addc_u32 s47, s47, 0
	global_load_dwordx4 v[212:215], v143, s[46:47]
	s_add_u32 s46, s46, 0x4000
	s_addc_u32 s47, s47, 0
	global_load_dwordx4 v[216:219], v143, s[46:47]
	s_mov_b64 s[46:47], s[40:41]
	global_load_dwordx4 v[220:223], v181, s[46:47]
	s_add_u32 s46, s46, 0x1000
	s_addc_u32 s47, s47, 0
	global_load_dwordx4 v[224:227], v181, s[46:47]
	s_add_u32 s46, s46, 0x1000
	s_addc_u32 s47, s47, 0
	global_load_dwordx4 v[228:231], v181, s[46:47]
	s_add_u32 s46, s46, 0x1000
	s_addc_u32 s47, s47, 0
	global_load_dwordx4 v[232:235], v181, s[46:47]
	s_mov_b64 s[46:47], s[42:43]
	global_load_dwordx4 v[236:239], v181, s[46:47]
	s_add_u32 s46, s46, 0x1000
	s_addc_u32 s47, s47, 0
	global_load_dwordx4 v[240:243], v181, s[46:47]
	s_cmp_lt_u32 s26, 127
	s_cselect_b32 s8, 0x10000, 0
	s_cselect_b32 s12, 0x4000, 0
	s_cselect_b32 s13, 0x2000, 0
	s_addc_u32 s26, s26, 0
	s_add_u32 s36, s36, s8
	s_addc_u32 s37, s37, 0
	s_add_u32 s38, s38, s8
	s_addc_u32 s39, s39, 0
	s_add_u32 s40, s40, s12
	s_addc_u32 s41, s41, 0
	s_add_u32 s42, s42, s13
	s_addc_u32 s43, s43, 0
	s_movk_i32 s30, 32
; #define GS_BAR() asm volatile("s_waitcnt lgkmcnt(0)\n\ts_barrier" ::: "memory")
; __device__ __forceinline__ void gdn_scan_item(const Ctx& a, int l, int b, int h, int half, LAS unsigned char* lds, int variant) {
;     ...
;     if (loader) {
;         for (int n = 0; n < 128; n += 2) {
;             const int c2 = (n + 2 < 128) ? n + 2 : 127, c3 = (n + 3 < 128) ? n + 3 : 127;
;             if (variant != 1) { GS_LOAD(c2, pfA); GS_STORE(1, pfB); }
;             GS_BAR();
;             if (variant != 1) { GS_LOAD(c3, pfB); GS_STORE(0, pfA); }
;             GS_BAR();
;         }
.Lld_loop:
	s_mov_b64 s[46:47], s[36:37]
	global_load_dwordx4 v[2:5], v143, s[46:47]
	s_add_u32 s46, s46, 0x4000
	s_addc_u32 s47, s47, 0
	global_load_dwordx4 v[6:9], v143, s[46:47]
	s_add_u32 s46, s46, 0x4000
	s_addc_u32 s47, s47, 0
	global_load_dwordx4 v[10:13], v143, s[46:47]
	s_add_u32 s46, s46, 0x4000
	s_addc_u32 s47, s47, 0
	global_load_dwordx4 v[14:17], v143, s[46:47]
	s_mov_b64 s[46:47], s[38:39]
	global_load_dwordx4 v[18:21], v143, s[46:47]
	s_add_u32 s46, s46, 0x4000
	s_addc_u32 s47, s47, 0
	global_load_dwordx4 v[22:25], v143, s[46:47]
	s_add_u32 s46, s46, 0x4000
	s_addc_u32 s47, s47, 0
	global_load_dwordx4 v[26:29], v143, s[46:47]
	s_add_u32 s46, s46, 0x4000
	s_addc_u32 s47, s47, 0
	global_load_dwordx4 v[30:33], v143, s[46:47]
	s_mov_b64 s[46:47], s[40:41]
	global_load_dwordx4 v[34:37], v181, s[46:47]
	s_add_u32 s46, s46, 0x1000
	s_addc_u32 s47, s47, 0
	global_load_dwordx4 v[38:41], v181, s[46:47]
	s_add_u32 s46, s46, 0x1000
	s_addc_u32 s47, s47, 0
	global_load_dwordx4 v[42:45], v181, s[46:47]
	s_add_u32 s46, s46, 0x1000
	s_addc_u32 s47, s47, 0
	global_load_dwordx4 v[46:49], v181, s[46:47]
	s_mov_b64 s[46:47], s[42:43]
	global_load_dwordx4 v[50:53], v181, s[46:47]
	s_add_u32 s46, s46, 0x1000
	s_addc_u32 s47, s47, 0
	global_load_dwordx4 v[54:57], v181, s[46:47]
	s_cmp_lt_u32 s26, 127
	s_cselect_b32 s8, 0x10000, 0
	s_cselect_b32 s12, 0x4000, 0
	s_cselect_b32 s13, 0x2000, 0
	s_addc_u32 s26, s26, 0
	s_add_u32 s36, s36, s8
	s_addc_u32 s37, s37, 0
	s_add_u32 s38, s38, s8
	s_addc_u32 s39, s39, 0
	s_add_u32 s40, s40, s12
	s_addc_u32 s41, s41, 0
	s_add_u32 s42, s42, s13
	s_addc_u32 s43, s43, 0
	s_waitcnt vmcnt(42)
	ds_write2_b64 v1, v[58:59], v[60:61] offset1:1
	v_add_u32_e32 v193, 0x1080, v1
	ds_write2_b64 v193, v[62:63], v[64:65] offset1:1
	v_add_u32_e32 v192, 0x2100, v1
	ds_write2_b64 v192, v[66:67], v[68:69] offset1:1
	v_add_u32_e32 v193, 0x3180, v1
	ds_write2_b64 v193, v[70:71], v[72:73] offset1:1
	v_add_u32_e32 v192, 0x4200, v1
	ds_write2_b64 v192, v[74:75], v[76:77] offset1:1
	v_add_u32_e32 v193, 0x5280, v1
	ds_write2_b64 v193, v[78:79], v[80:81] offset1:1
	v_add_u32_e32 v192, 0x6300, v1
	ds_write2_b64 v192, v[82:83], v[84:85] offset1:1
	v_add_u32_e32 v193, 0x7380, v1
	ds_write2_b64 v193, v[86:87], v[88:89] offset1:1
	ds_write2_b64 v142, v[90:91], v[92:93] offset1:1
	v_add_u32_e32 v193, 0x1100, v142
	ds_write2_b64 v193, v[94:95], v[96:97] offset1:1
	v_add_u32_e32 v192, 0x2200, v142
	ds_write2_b64 v192, v[98:99], v[100:101] offset1:1
	v_add_u32_e32 v193, 0x3300, v142
	ds_write2_b64 v193, v[102:103], v[104:105] offset1:1
	v_add_u32_e32 v192, 0x4400, v142
	ds_write2_b64 v192, v[106:107], v[108:109] offset1:1
	v_add_u32_e32 v193, 0x5500, v142
	ds_write2_b64 v193, v[110:111], v[112:113] offset1:1
	v_subrev_u32_e32 v1, 0xea00, v1
	v_subrev_u32_e32 v142, 0xea00, v142
	s_waitcnt lgkmcnt(0)
	s_barrier
	s_mov_b64 s[46:47], s[36:37]
	global_load_dwordx4 v[58:61], v143, s[46:47]
	s_add_u32 s46, s46, 0x4000
	s_addc_u32 s47, s47, 0
	global_load_dwordx4 v[62:65], v143, s[46:47]
	s_add_u32 s46, s46, 0x4000
	s_addc_u32 s47, s47, 0
	global_load_dwordx4 v[66:69], v143, s[46:47]
	s_add_u32 s46, s46, 0x4000
	s_addc_u32 s47, s47, 0
	global_load_dwordx4 v[70:73], v143, s[46:47]
	s_mov_b64 s[46:47], s[38:39]
	global_load_dwordx4 v[74:77], v143, s[46:47]
	s_add_u32 s46, s46, 0x4000
	s_addc_u32 s47, s47, 0
	global_load_dwordx4 v[78:81], v143, s[46:47]
	s_add_u32 s46, s46, 0x4000
	s_addc_u32 s47, s47, 0
	global_load_dwordx4 v[82:85], v143, s[46:47]
	s_add_u32 s46, s46, 0x4000
	s_addc_u32 s47, s47, 0
	global_load_dwordx4 v[86:89], v143, s[46:47]
	s_mov_b64 s[46:47], s[40:41]
	global_load_dwordx4 v[90:93], v181, s[46:47]
	s_add_u32 s46, s46, 0x1000
	s_addc_u32 s47, s47, 0
	global_load_dwordx4 v[94:97], v181, s[46:47]
	s_add_u32 s46, s46, 0x1000
	s_addc_u32 s47, s47, 0
	global_load_dwordx4 v[98:101], v181, s[46:47]
	s_add_u32 s46, s46, 0x1000
	s_addc_u32 s47, s47, 0
	global_load_dwordx4 v[102:105], v181, s[46:47]
	s_mov_b64 s[46:47], s[42:43]
	global_load_dwordx4 v[106:109], v181, s[46:47]
	s_add_u32 s46, s46, 0x1000
	s_addc_u32 s47, s47, 0
	global_load_dwordx4 v[110:113], v181, s[46:47]
	s_cmp_lt_u32 s26, 127
	s_cselect_b32 s8, 0x10000, 0
	s_cselect_b32 s12, 0x4000, 0
	s_cselect_b32 s13, 0x2000, 0
	s_addc_u32 s26, s26, 0
	s_add_u32 s36, s36, s8
	s_addc_u32 s37, s37, 0
	s_add_u32 s38, s38, s8
	s_addc_u32 s39, s39, 0
	s_add_u32 s40, s40, s12
	s_addc_u32 s41, s41, 0
	s_add_u32 s42, s42, s13
	s_addc_u32 s43, s43, 0
	s_waitcnt vmcnt(42)
	ds_write2_b64 v1, v[114:115], v[116:117] offset1:1
	v_add_u32_e32 v193, 0x1080, v1
	ds_write2_b64 v193, v[118:119], v[120:121] offset1:1
	v_add_u32_e32 v192, 0x2100, v1
	ds_write2_b64 v192, v[122:123], v[124:125] offset1:1
	v_add_u32_e32 v193, 0x3180, v1
	ds_write2_b64 v193, v[126:127], v[128:129] offset1:1
	v_add_u32_e32 v192, 0x4200, v1
	ds_write2_b64 v192, v[130:131], v[132:133] offset1:1
	v_add_u32_e32 v193, 0x5280, v1
	ds_write2_b64 v193, v[134:135], v[136:137] offset1:1
	v_add_u32_e32 v192, 0x6300, v1
	ds_write2_b64 v192, v[138:139], v[140:141] offset1:1
	v_add_u32_e32 v193, 0x7380, v1
	ds_write2_b64 v193, v[146:147], v[148:149] offset1:1
	ds_write2_b64 v142, v[150:151], v[152:153] offset1:1
	v_add_u32_e32 v193, 0x1100, v142
	ds_write2_b64 v193, v[154:155], v[156:157] offset1:1
	v_add_u32_e32 v192, 0x2200, v142
	ds_write2_b64 v192, v[158:159], v[160:161] offset1:1
	v_add_u32_e32 v193, 0x3300, v142
	ds_write2_b64 v193, v[162:163], v[164:165] offset1:1
	v_add_u32_e32 v192, 0x4400, v142
	ds_write2_b64 v192, v[166:167], v[168:169] offset1:1
	v_add_u32_e32 v193, 0x5500, v142
	ds_write2_b64 v193, v[170:171], v[172:173] offset1:1
	v_add_u32_e32 v1, 0xea00, v1
	v_add_u32_e32 v142, 0xea00, v142
	s_waitcnt lgkmcnt(0)
	s_barrier
; #define GS_BAR() asm volatile("s_waitcnt lgkmcnt(0)\n\ts_barrier" ::: "memory")
; __device__ __forceinline__ void gdn_scan_item(const Ctx& a, int l, int b, int h, int half, LAS unsigned char* lds, int variant) {
;     ...
;     if (loader) {
;         for (int n = 0; n < 128; n += 2) {
;             const int c2 = (n + 2 < 128) ? n + 2 : 127, c3 = (n + 3 < 128) ? n + 3 : 127;
;             if (variant != 1) { GS_LOAD(c2, pfA); GS_STORE(1, pfB); }
;             GS_BAR();
;             if (variant != 1) { GS_LOAD(c3, pfB); GS_STORE(0, pfA); }
;             GS_BAR();
;         }
	s_mov_b64 s[46:47], s[36:37]
	global_load_dwordx4 v[114:117], v143, s[46:47]
	s_add_u32 s46, s46, 0x4000
	s_addc_u32 s47, s47, 0
	global_load_dwordx4 v[118:121], v143, s[46:47]
	s_add_u32 s46, s46, 0x4000
	s_addc_u32 s47, s47, 0
	global_load_dwordx4 v[122:125], v143, s[46:47]
	s_add_u32 s46, s46, 0x4000
	s_addc_u32 s47, s47, 0
	global_load_dwordx4 v[126:129], v143, s[46:47]
	s_mov_b64 s[46:47], s[38:39]
	global_load_dwordx4 v[130:133], v143, s[46:47]
	s_add_u32 s46, s46, 0x4000
	s_addc_u32 s47, s47, 0
	global_load_dwordx4 v[134:137], v143, s[46:47]
	s_add_u32 s46, s46, 0x4000
	s_addc_u32 s47, s47, 0
	global_load_dwordx4 v[138:141], v143, s[46:47]
	s_add_u32 s46, s46, 0x4000
	s_addc_u32 s47, s47, 0
	global_load_dwordx4 v[146:149], v143, s[46:47]
	s_mov_b64 s[46:47], s[40:41]
	global_load_dwordx4 v[150:153], v181, s[46:47]
	s_add_u32 s46, s46, 0x1000
	s_addc_u32 s47, s47, 0
	global_load_dwordx4 v[154:157], v181, s[46:47]
	s_add_u32 s46, s46, 0x1000
	s_addc_u32 s47, s47, 0
	global_load_dwordx4 v[158:161], v181, s[46:47]
	s_add_u32 s46, s46, 0x1000
	s_addc_u32 s47, s47, 0
	global_load_dwordx4 v[162:165], v181, s[46:47]
	s_mov_b64 s[46:47], s[42:43]
	global_load_dwordx4 v[166:169], v181, s[46:47]
	s_add_u32 s46, s46, 0x1000
	s_addc_u32 s47, s47, 0
	global_load_dwordx4 v[170:173], v181, s[46:47]
	s_cmp_lt_u32 s26, 127
	s_cselect_b32 s8, 0x10000, 0
	s_cselect_b32 s12, 0x4000, 0
	s_cselect_b32 s13, 0x2000, 0
	s_addc_u32 s26, s26, 0
	s_add_u32 s36, s36, s8
	s_addc_u32 s37, s37, 0
	s_add_u32 s38, s38, s8
	s_addc_u32 s39, s39, 0
	s_add_u32 s40, s40, s12
	s_addc_u32 s41, s41, 0
	s_add_u32 s42, s42, s13
	s_addc_u32 s43, s43, 0
	s_waitcnt vmcnt(42)
	ds_write2_b64 v1, v[174:175], v[176:177] offset1:1
	v_add_u32_e32 v193, 0x1080, v1
	ds_write2_b64 v193, v[184:185], v[186:187] offset1:1
	v_add_u32_e32 v192, 0x2100, v1
	ds_write2_b64 v192, v[188:189], v[190:191] offset1:1
	v_add_u32_e32 v193, 0x3180, v1
	ds_write2_b64 v193, v[200:201], v[202:203] offset1:1
	v_add_u32_e32 v192, 0x4200, v1
	ds_write2_b64 v192, v[204:205], v[206:207] offset1:1
	v_add_u32_e32 v193, 0x5280, v1
	ds_write2_b64 v193, v[208:209], v[210:211] offset1:1
	v_add_u32_e32 v192, 0x6300, v1
	ds_write2_b64 v192, v[212:213], v[214:215] offset1:1
	v_add_u32_e32 v193, 0x7380, v1
	ds_write2_b64 v193, v[216:217], v[218:219] offset1:1
	ds_write2_b64 v142, v[220:221], v[222:223] offset1:1
	v_add_u32_e32 v193, 0x1100, v142
	ds_write2_b64 v193, v[224:225], v[226:227] offset1:1
	v_add_u32_e32 v192, 0x2200, v142
	ds_write2_b64 v192, v[228:229], v[230:231] offset1:1
	v_add_u32_e32 v193, 0x3300, v142
	ds_write2_b64 v193, v[232:233], v[234:235] offset1:1
	v_add_u32_e32 v192, 0x4400, v142
	ds_write2_b64 v192, v[236:237], v[238:239] offset1:1
	v_add_u32_e32 v193, 0x5500, v142
	ds_write2_b64 v193, v[240:241], v[242:243] offset1:1
	v_subrev_u32_e32 v1, 0xea00, v1
	v_subrev_u32_e32 v142, 0xea00, v142
	s_waitcnt lgkmcnt(0)
	s_barrier
	s_mov_b64 s[46:47], s[36:37]
	global_load_dwordx4 v[174:177], v143, s[46:47]
	s_add_u32 s46, s46, 0x4000
	s_addc_u32 s47, s47, 0
	global_load_dwordx4 v[184:187], v143, s[46:47]
	s_add_u32 s46, s46, 0x4000
	s_addc_u32 s47, s47, 0
	global_load_dwordx4 v[188:191], v143, s[46:47]
	s_add_u32 s46, s46, 0x4000
	s_addc_u32 s47, s47, 0
	global_load_dwordx4 v[200:203], v143, s[46:47]
	s_mov_b64 s[46:47], s[38:39]
	global_load_dwordx4 v[204:207], v143, s[46:47]
	s_add_u32 s46, s46, 0x4000
	s_addc_u32 s47, s47, 0
	global_load_dwordx4 v[208:211], v143, s[46:47]
	s_add_u32 s46, s46, 0x4000
	s_addc_u32 s47, s47, 0
	global_load_dwordx4 v[212:215], v143, s[46:47]
	s_add_u32 s46, s46, 0x4000
	s_addc_u32 s47, s47, 0
	global_load_dwordx4 v[216:219], v143, s[46:47]
	s_mov_b64 s[46:47], s[40:41]
	global_load_dwordx4 v[220:223], v181, s[46:47]
	s_add_u32 s46, s46, 0x1000
	s_addc_u32 s47, s47, 0
	global_load_dwordx4 v[224:227], v181, s[46:47]
	s_add_u32 s46, s46, 0x1000
	s_addc_u32 s47, s47, 0
	global_load_dwordx4 v[228:231], v181, s[46:47]
	s_add_u32 s46, s46, 0x1000
	s_addc_u32 s47, s47, 0
	global_load_dwordx4 v[232:235], v181, s[46:47]
	s_mov_b64 s[46:47], s[42:43]
	global_load_dwordx4 v[236:239], v181, s[46:47]
	s_add_u32 s46, s46, 0x1000
	s_addc_u32 s47, s47, 0
	global_load_dwordx4 v[240:243], v181, s[46:47]
	s_cmp_lt_u32 s26, 127
	s_cselect_b32 s8, 0x10000, 0
	s_cselect_b32 s12, 0x4000, 0
	s_cselect_b32 s13, 0x2000, 0
	s_addc_u32 s26, s26, 0
	s_add_u32 s36, s36, s8
	s_addc_u32 s37, s37, 0
	s_add_u32 s38, s38, s8
	s_addc_u32 s39, s39, 0
	s_add_u32 s40, s40, s12
	s_addc_u32 s41, s41, 0
	s_add_u32 s42, s42, s13
	s_addc_u32 s43, s43, 0
	s_waitcnt vmcnt(42)
	ds_write2_b64 v1, v[2:3], v[4:5] offset1:1
	v_add_u32_e32 v193, 0x1080, v1
	ds_write2_b64 v193, v[6:7], v[8:9] offset1:1
	v_add_u32_e32 v192, 0x2100, v1
	ds_write2_b64 v192, v[10:11], v[12:13] offset1:1
	v_add_u32_e32 v193, 0x3180, v1
	ds_write2_b64 v193, v[14:15], v[16:17] offset1:1
	v_add_u32_e32 v192, 0x4200, v1
	ds_write2_b64 v192, v[18:19], v[20:21] offset1:1
	v_add_u32_e32 v193, 0x5280, v1
	ds_write2_b64 v193, v[22:23], v[24:25] offset1:1
	v_add_u32_e32 v192, 0x6300, v1
	ds_write2_b64 v192, v[26:27], v[28:29] offset1:1
	v_add_u32_e32 v193, 0x7380, v1
	ds_write2_b64 v193, v[30:31], v[32:33] offset1:1
	ds_write2_b64 v142, v[34:35], v[36:37] offset1:1
	v_add_u32_e32 v193, 0x1100, v142
	ds_write2_b64 v193, v[38:39], v[40:41] offset1:1
	v_add_u32_e32 v192, 0x2200, v142
	ds_write2_b64 v192, v[42:43], v[44:45] offset1:1
	v_add_u32_e32 v193, 0x3300, v142
	ds_write2_b64 v193, v[46:47], v[48:49] offset1:1
	v_add_u32_e32 v192, 0x4400, v142
	ds_write2_b64 v192, v[50:51], v[52:53] offset1:1
	v_add_u32_e32 v193, 0x5500, v142
	ds_write2_b64 v193, v[54:55], v[56:57] offset1:1
	v_add_u32_e32 v1, 0xea00, v1
	v_add_u32_e32 v142, 0xea00, v142
	s_waitcnt lgkmcnt(0)
	s_barrier
	s_sub_u32 s30, s30, 1
	s_cmp_eq_u32 s30, 0
	s_cbranch_scc0 .Lld_loop
	s_waitcnt vmcnt(0)
